# v39 + P0 work shift: last 8192 w_in tiles converted by the 64 WGs idle in P1 partial last round (re-enter P0 static loop), P0 static part 15 tiles per wave
# speedup vs baseline: 1.0076x; 1.0076x over previous
; #define LAS __attribute__((address_space(3)))
; #define REFRESH_IDS() do { lane = fresh_lane(); tid = wave * 64 + lane; } while (0)
; __global__ void __launch_bounds__(NWAVES * 64, 2) fwd(Args args) {
;     ...
;     if (IN(0)) {
;         REFRESH_IDS();
;         LAS float* scr = (LAS float*)(L + wave * (64 * 65 * 4));
;         const int NS0 = ((NI0 / 32 * 27) / NGW) * NGW;
;         P0_RUN(gw, NS0, NGW);
.Lhlp_entry:
	s_lshl_b32 s4, s75, 3
	s_add_i32 s16, s4, s28
	s_lshl_b32 s18, s33, 3
	s_add_u32 s6, s14, 0x40000
	s_addc_u32 s7, s15, 0
	s_add_u32 s36, s14, 0x400000
	s_addc_u32 s37, s15, 0
	s_add_u32 s34, s14, 0xb400000
	s_addc_u32 s35, s15, 0
	s_load_dwordx2 s[96:97], s[0:1], 0x98
	s_add_u32 s10, s14, 0x10c00000
	s_addc_u32 s11, s15, 0
	s_add_u32 s26, s14, 0x2a800000
	s_addc_u32 s27, s15, 0
	s_waitcnt lgkmcnt(0)
	s_cmp_lt_i32 s96, 1
	s_cselect_b64 s[4:5], -1, 0
	s_cmp_gt_i32 s97, 0
	s_cselect_b64 s[20:21], -1, 0
	s_and_b64 s[4:5], s[4:5], s[20:21]
	s_and_b64 vcc, exec, s[4:5]
	s_mul_i32 s74, s28, 0x4100
	s_cbranch_vccz .LBB0_219
	s_abs_i32 s4, s18
	v_cvt_f32_u32_e32 v0, s4
	s_sub_i32 s5, 0, s4
	s_add_i32 s19, s74, 0
	v_mbcnt_lo_u32_b32 v140, -1, 0
	v_mbcnt_hi_u32_b32 v140, -1, v140
	v_rcp_iflag_f32_e32 v0, v0
	s_nop 0
	v_mul_f32_e32 v0, 0x4f7ffffe, v0
	v_cvt_u32_f32_e32 v0, v0
	s_nop 0
	v_readfirstlane_b32 s17, v0
	s_mul_i32 s5, s5, s17
	s_mul_hi_u32 s5, s17, s5
	s_add_i32 s17, s17, s5
	s_mul_hi_u32 s5, s17, 0x7c4e
	s_mul_i32 s5, s5, s4
	s_sub_i32 s5, 0x7c4e, s5
	s_sub_i32 s17, s5, s4
	s_cmp_ge_u32 s5, s4
	s_cselect_b32 s5, s17, s5
	s_sub_i32 s17, s5, s4
	s_cmp_ge_u32 s5, s4
	s_cselect_b32 s23, s17, s5
	s_sub_i32 s22, 0x7c4e, s23
	s_cmp_lg_u32 s33, 64
	s_cbranch_scc1 .Lhlp_noovr
	s_add_i32 s16, s16, 0x9940
	s_mov_b32 s22, 0xb940
.Lhlp_noovr:
	s_cmp_ge_i32 s16, s22
	s_cbranch_scc1 .LBB0_84
	s_cmpk_gt_i32 s16, 0x55ff
	s_cbranch_scc0 .LBB0_14
	s_cmpk_gt_u32 s16, 0x80ff
	s_cbranch_scc0 .LBB0_15
	s_add_u32 s42, s0, 48
	s_addc_u32 s43, s1, 0
	s_add_i32 s17, s16, 0x7f00
	s_and_b32 s20, s17, 0xffff
	s_mul_i32 s20, s20, 0x91a3
	s_load_dwordx2 s[4:5], s[0:1], 0x28
	s_lshr_b32 s20, s20, 23
	s_lshl_b32 s30, s20, 6
	s_mulk_i32 s20, 0xe1
	s_sub_i32 s17, s17, s20
	s_lshl_b32 s17, s17, 6
	s_and_b32 s17, s17, 0xffc0
	s_cbranch_execz .LBB0_16
	s_movk_i32 s25, 0x1040
	s_movk_i32 s24, 0x3820
	s_mov_b64 s[40:41], s[10:11]
	s_branch .LBB0_17

; #define XL(V, ROW) do { const int r_ = (ROW) < M ? (ROW) : M - 1; const f32x4* p_ = (const f32x4*)(x + (size_t)r_ * D) + lane; _Pragma("unroll") for (int j = 0; j < 16; ++j) V[j] = p_[64 * j]; } while (0)
; __global__ void __launch_bounds__(NWAVES * 64, 2) fwd(Args args) {
;     ...
;         { f32x4 xa[16], xb[16];
;     ...
;           XL(xa, gw);
;           for (int row = gw; row < M; row += 2 * NGW) { XL(xb, row + NGW); XP(xa, row); XL(xa, row + 2 * NGW); XP(xb, row + NGW); }
.LBB0_84:
	s_cmp_eq_u32 s33, 64
	s_cbranch_scc1 .Lhlp_return
	s_cmpk_gt_i32 s16, 0x1fff
	s_cbranch_scc1 .LBB0_93
	s_ashr_i32 s17, s16, 31
	s_lshl_b64 s[4:5], s[16:17], 14
	v_ashrrev_i32_e32 v141, 31, v140
	s_add_u32 s4, s2, s4
	v_lshlrev_b64 v[28:29], 4, v[140:141]
	s_addc_u32 s5, s3, s5
	v_lshl_add_u64 v[30:31], s[4:5], 0, v[28:29]
	v_add_co_u32_e32 v16, vcc, 0x3000, v30
	v_lshl_add_u64 v[128:129], s[2:3], 0, v[28:29]
	s_nop 0
	v_addc_co_u32_e32 v17, vcc, 0, v31, vcc
	v_add_co_u32_e32 v32, vcc, 0x2000, v30
	global_load_dwordx4 v[0:3], v[16:17], off offset:3072
	global_load_dwordx4 v[4:7], v[16:17], off offset:2048
	global_load_dwordx4 v[8:11], v[16:17], off offset:1024
	global_load_dwordx4 v[12:15], v[16:17], off
	v_addc_co_u32_e32 v33, vcc, 0, v31, vcc
	global_load_dwordx4 v[16:19], v[32:33], off offset:3072
	global_load_dwordx4 v[20:23], v[32:33], off offset:2048
	global_load_dwordx4 v[24:27], v[32:33], off offset:1024
	global_load_dwordx4 v[56:59], v[32:33], off
	v_add_co_u32_e32 v32, vcc, 0x1000, v30
	v_lshlrev_b32_e32 v28, 2, v140
	s_nop 0
	v_addc_co_u32_e32 v33, vcc, 0, v31, vcc
	global_load_dwordx4 v[60:63], v[32:33], off offset:3072
	global_load_dwordx4 v[64:67], v[32:33], off offset:2048
	global_load_dwordx4 v[68:71], v[32:33], off offset:1024
	global_load_dwordx4 v[76:79], v[32:33], off
	global_load_dwordx4 v[80:83], v[30:31], off offset:3072
	global_load_dwordx4 v[92:95], v[30:31], off offset:2048
	global_load_dwordx4 v[100:103], v[30:31], off offset:1024
	global_load_dwordx4 v[104:107], v[30:31], off
	v_ashrrev_i32_e32 v29, 31, v28
	v_lshl_add_u64 v[130:131], v[28:29], 1, s[26:27]
	v_mbcnt_lo_u32_b32 v28, -1, 0
	s_movk_i32 s17, 0x3000
	s_movk_i32 s20, 0x2000
	s_movk_i32 s21, 0x1000
	v_cmp_eq_u32_e64 s[2:3], 0, v140
	s_lshl_b32 s24, s33, 4
	v_mov_b32_e32 v134, 0
	v_mov_b32_e32 v135, 0x2080
	v_mbcnt_hi_u32_b32 v136, -1, v28
	s_mov_b32 s38, s16
	s_branch .LBB0_88

; #define LDS_BAR() do { asm volatile("s_waitcnt lgkmcnt(0)" ::: "memory"); __builtin_amdgcn_s_barrier(); asm volatile("" ::: "memory"); } while (0)
; #define LAS __attribute__((address_space(3)))
; #define REFRESH_IDS() do { lane = fresh_lane(); tid = wave * 64 + lane; } while (0)
; __global__ void __launch_bounds__(NWAVES * 64, 2) fwd(Args args) {
;     ...
;           for (unsigned it = 0u;; ++it) {
;               LDS_BAR();
;               const unsigned q = MISC[16 + (it & 1u)]; if (q >= NTB) break;
;               if (tid == 0) { int z = 0; asm volatile("" : "+v"(z)); qpre = __hip_atomic_fetch_add(ctl + CW_AQ + 64 + z, 1u, __ATOMIC_RELAXED, __HIP_MEMORY_SCOPE_AGENT); }
;               volatile LAS unsigned* qslot = MISC + 16 + ((it + 1u) & 1u);
;               REFRESH_IDS();
;               int t0 = NS0 + (int)q * 16 + wave, t1 = t0 + 8; t0 = t0 < NI0 - 1 ? t0 : NI0 - 1; t1 = t1 < NI0 - 1 ? t1 : NI0 - 1;
;               f32x4 va[16], vb[16]; P0T_DECL(a); P0T_DECL(b);
;               P0T_RESOLVE(a, t0); p0_load(aW, aN, ak0, an0, lane, va);
.LBB0_103:
	s_or_b64 exec, exec, s[46:47]
	s_lshl_b32 s23, s23, 4
	s_add_i32 s23, s20, s23
	s_min_i32 s24, s23, 0x993f
	s_cmpk_gt_u32 s23, 0x55ff
	v_mbcnt_lo_u32_b32 v140, -1, 0
	v_mbcnt_hi_u32_b32 v140, -1, v140
	s_cbranch_scc0 .LBB0_108
	s_cmpk_gt_u32 s23, 0x80ff
	s_mov_b64 s[46:47], -1
	s_cbranch_scc0 .LBB0_106
	s_add_i32 s25, s24, 0xffff7f00
	s_mul_hi_u32 s29, s25, 0x91a2b3c5
	s_lshr_b32 s29, s29, 7
	s_lshl_b32 s56, s29, 6
	s_mulk_i32 s29, 0xe1
	s_sub_i32 s25, s25, s29
	s_lshl_b32 s67, s25, 6
	s_mov_b64 s[46:47], 0
	s_mov_b64 s[60:61], s[40:41]

; __device__ __forceinline__ void p0_load(const float* W, int N, int k0, int n0, int lane, f32x4 (&v)[16]) {
;     const int c = lane & 15, rq = lane >> 4;
;     int col = n0 + 4 * c; col = col < N - 4 ? col : N - 4;
;     const float* p = W + (size_t)(k0 + rq) * N + col;
; #pragma unroll
;     for (int j = 0; j < 16; ++j) v[j] = __builtin_nontemporal_load((const f32x4*)(p + (size_t)(4 * j) * N));
; }
; __global__ void __launch_bounds__(NWAVES * 64, 2) fwd(Args args) {
;     ...
;               int t0 = NS0 + (int)q * 16 + wave, t1 = t0 + 8; t0 = t0 < NI0 - 1 ? t0 : NI0 - 1; t1 = t1 < NI0 - 1 ? t1 : NI0 - 1;
;               f32x4 va[16], vb[16]; P0T_DECL(a); P0T_DECL(b);
;               P0T_RESOLVE(a, t0); p0_load(aW, aN, ak0, an0, lane, va);
;               P0T_RESOLVE(b, t1); p0_load(bW, bN, bk0, bn0, lane, vb);
.LBB0_112:
	v_ashrrev_i32_e32 v142, 4, v140
	s_load_dwordx2 s[24:25], s[46:47], 0x0
	v_add_u32_e32 v1, s56, v142
	v_lshlrev_b32_e32 v0, 2, v140
	v_mad_u64_u32 v[2:3], s[46:47], v1, s68, 0
	v_and_b32_e32 v143, 60, v0
	v_ashrrev_i32_e32 v5, 31, v1
	v_mov_b32_e32 v4, v3
	v_or_b32_e32 v0, s67, v143
	s_add_i32 s29, s68, -4
	v_mad_u64_u32 v[4:5], s[46:47], v5, s68, v[4:5]
	v_min_i32_e32 v0, s29, v0
	v_mov_b32_e32 v3, v4
	s_waitcnt lgkmcnt(0)
	v_lshl_add_u64 v[2:3], v[2:3], 2, s[24:25]
	v_ashrrev_i32_e32 v1, 31, v0
	v_lshl_add_u64 v[0:1], v[0:1], 2, v[2:3]
	s_lshl_b32 s44, s68, 2
	v_lshl_add_u64 v[2:3], s[44:45], 2, v[0:1]
	s_lshl_b32 s44, s68, 3
	global_load_dwordx4 v[76:79], v[0:1], off nt
	global_load_dwordx4 v[72:75], v[2:3], off nt
	v_lshl_add_u64 v[2:3], s[44:45], 2, v[0:1]
	s_mul_i32 s44, s68, 12
	v_lshl_add_u64 v[4:5], s[44:45], 2, v[0:1]
	s_lshl_b32 s44, s68, 4
	global_load_dwordx4 v[84:87], v[2:3], off nt
	global_load_dwordx4 v[80:83], v[4:5], off nt
	v_lshl_add_u64 v[2:3], s[44:45], 2, v[0:1]
	s_mul_i32 s44, s68, 20
	v_lshl_add_u64 v[4:5], s[44:45], 2, v[0:1]
	s_mul_i32 s44, s68, 24
	global_load_dwordx4 v[92:95], v[2:3], off nt
	global_load_dwordx4 v[88:91], v[4:5], off nt
	v_lshl_add_u64 v[2:3], s[44:45], 2, v[0:1]
	s_mul_i32 s44, s68, 28
	v_lshl_add_u64 v[4:5], s[44:45], 2, v[0:1]
	s_lshl_b32 s44, s68, 5
	global_load_dwordx4 v[100:103], v[2:3], off nt
	global_load_dwordx4 v[96:99], v[4:5], off nt
	v_lshl_add_u64 v[2:3], s[44:45], 2, v[0:1]
	s_mul_i32 s44, s68, 36
	v_lshl_add_u64 v[4:5], s[44:45], 2, v[0:1]
	s_mul_i32 s44, s68, 40
	global_load_dwordx4 v[108:111], v[2:3], off nt
	global_load_dwordx4 v[104:107], v[4:5], off nt
	v_lshl_add_u64 v[2:3], s[44:45], 2, v[0:1]
	s_mul_i32 s44, s68, 44
	v_lshl_add_u64 v[4:5], s[44:45], 2, v[0:1]
	s_mul_i32 s44, s68, 48
	global_load_dwordx4 v[116:119], v[2:3], off nt
	global_load_dwordx4 v[112:115], v[4:5], off nt
	v_lshl_add_u64 v[2:3], s[44:45], 2, v[0:1]
	s_mul_i32 s44, s68, 52
	v_lshl_add_u64 v[4:5], s[44:45], 2, v[0:1]
	s_mul_i32 s44, s68, 56
	global_load_dwordx4 v[124:127], v[2:3], off nt
	global_load_dwordx4 v[120:123], v[4:5], off nt
	v_lshl_add_u64 v[2:3], s[44:45], 2, v[0:1]
	s_mul_i32 s44, s68, 60
	v_lshl_add_u64 v[0:1], s[44:45], 2, v[0:1]
	global_load_dwordx4 v[132:135], v[2:3], off nt
	global_load_dwordx4 v[128:131], v[0:1], off nt
	s_min_i32 s25, s23, 0x9937
	s_cmpk_gt_u32 s23, 0x55f7
	s_cbranch_scc0 .LBB0_117
	s_cmpk_gt_u32 s23, 0x80f7
	s_mov_b64 s[46:47], -1
	s_cbranch_scc0 .LBB0_115
	s_add_i32 s23, s25, 0xffff7f08
	s_mul_hi_u32 s24, s23, 0x91a2b3c5
	s_lshr_b32 s24, s24, 7
	s_lshl_b32 s50, s24, 6
	s_mulk_i32 s24, 0xe1
	s_sub_i32 s23, s23, s24
	s_lshl_b32 s23, s23, 6
	s_mov_b64 s[46:47], 0
	s_mov_b64 s[54:55], s[40:41]

; #define REFRESH_IDS() do { lane = fresh_lane(); tid = wave * 64 + lane; } while (0)
; #define GRID_BAR() xcd_barrier(bar)
; #define GRID_BAR() do { } while (0)
; #define BOTH(k) (IN(k) && IN((k) + 1))
; __global__ void __launch_bounds__(NWAVES * 64, 2) fwd(Args args) {
;     ...
;     if (IN(1)) {
;         REFRESH_IDS();
;         pg8::Gemm g{XB, Wgu1, M, 2 * FF, D, LDD, LDD}; pg8::StaticOrder S; S.init(M, 2 * FF, G, bx);
;         pg8::EpiGateUp E{ACT, ssq};
;         pg8::gemm_phase<pg8::EpiGateUp, pg8::StaticOrder, true, true>(L, g, S, E, wave);
;         if (BOTH(1)) GRID_BAR();
.LBB0_240:
	s_cmpk_lt_u32 s8, 0xc0
	s_cbranch_scc1 .Lhlp_done
	v_writelane_b32 v238, s0, 0
	v_writelane_b32 v238, s1, 1
	v_writelane_b32 v238, s2, 2
	v_writelane_b32 v238, s3, 3
	v_writelane_b32 v238, s4, 4
	v_writelane_b32 v238, s5, 5
	v_writelane_b32 v238, s6, 6
	v_writelane_b32 v238, s7, 7
	v_writelane_b32 v238, s8, 8
	v_writelane_b32 v238, s9, 9
	v_writelane_b32 v238, s10, 10
	v_writelane_b32 v238, s11, 11
	v_writelane_b32 v238, s12, 12
	v_writelane_b32 v238, s13, 13
	v_writelane_b32 v238, s14, 14
	v_writelane_b32 v238, s15, 15
	v_writelane_b32 v238, s16, 16
	v_writelane_b32 v238, s17, 17
	v_writelane_b32 v238, s18, 18
	v_writelane_b32 v238, s19, 19
	v_writelane_b32 v238, s20, 20
	v_writelane_b32 v238, s21, 21
	v_writelane_b32 v238, s22, 22
	v_writelane_b32 v238, s23, 23
	v_writelane_b32 v238, s24, 24
	v_writelane_b32 v238, s25, 25
	v_writelane_b32 v238, s26, 26
	v_writelane_b32 v238, s27, 27
	v_writelane_b32 v238, s28, 28
	v_writelane_b32 v238, s29, 29
	v_writelane_b32 v238, s30, 30
	v_writelane_b32 v238, s31, 31
	v_writelane_b32 v238, s32, 32
	v_writelane_b32 v238, s33, 33
	v_writelane_b32 v238, s34, 34
	v_writelane_b32 v238, s35, 35
	v_writelane_b32 v238, s36, 36
	v_writelane_b32 v238, s37, 37
	v_writelane_b32 v238, s38, 38
	v_writelane_b32 v238, s39, 39
	v_writelane_b32 v238, s40, 40
	v_writelane_b32 v238, s41, 41
	v_writelane_b32 v238, s42, 42
	v_writelane_b32 v238, s43, 43
	v_writelane_b32 v238, s44, 44
	v_writelane_b32 v238, s45, 45
	v_writelane_b32 v238, s46, 46
	v_writelane_b32 v238, s47, 47
	v_writelane_b32 v238, s48, 48
	v_writelane_b32 v238, s49, 49
	v_writelane_b32 v238, s50, 50
	v_writelane_b32 v238, s51, 51
	v_writelane_b32 v238, s52, 52
	v_writelane_b32 v238, s53, 53
	v_writelane_b32 v238, s54, 54
	v_writelane_b32 v238, s55, 55
	v_writelane_b32 v238, s56, 56
	v_writelane_b32 v238, s57, 57
	v_writelane_b32 v238, s58, 58
	v_writelane_b32 v238, s59, 59
	v_writelane_b32 v238, s60, 60
	v_writelane_b32 v238, s61, 61
	v_writelane_b32 v238, s62, 62
	v_writelane_b32 v238, s63, 63
	v_writelane_b32 v239, s64, 0
	v_writelane_b32 v239, s65, 1
	v_writelane_b32 v239, s66, 2
	v_writelane_b32 v239, s67, 3
	v_writelane_b32 v239, s68, 4
	v_writelane_b32 v239, s69, 5
	v_writelane_b32 v239, s70, 6
	v_writelane_b32 v239, s71, 7
	v_writelane_b32 v239, s72, 8
	v_writelane_b32 v239, s73, 9
	v_writelane_b32 v239, s74, 10
	v_writelane_b32 v239, s75, 11
	v_writelane_b32 v239, s76, 12
	v_writelane_b32 v239, s77, 13
	v_writelane_b32 v239, s78, 14
	v_writelane_b32 v239, s79, 15
	v_writelane_b32 v239, s80, 16
	v_writelane_b32 v239, s81, 17
	v_writelane_b32 v239, s82, 18
	v_writelane_b32 v239, s83, 19
	v_writelane_b32 v239, s84, 20
	v_writelane_b32 v239, s85, 21
	v_writelane_b32 v239, s86, 22
	v_writelane_b32 v239, s87, 23
	v_writelane_b32 v239, s88, 24
	v_writelane_b32 v239, s89, 25
	v_writelane_b32 v239, s90, 26
	v_writelane_b32 v239, s91, 27
	v_writelane_b32 v239, s92, 28
	v_writelane_b32 v239, s93, 29
	v_writelane_b32 v239, s94, 30
	v_writelane_b32 v239, s95, 31
	v_writelane_b32 v239, s96, 32
	v_writelane_b32 v239, s97, 33
	v_writelane_b32 v239, s98, 34
	v_writelane_b32 v239, s99, 35
	v_writelane_b32 v239, s100, 36
	v_writelane_b32 v239, s101, 37
	v_writelane_b32 v239, vcc_lo, 38
	v_writelane_b32 v239, vcc_hi, 39
	v_writelane_b32 v239, m0, 40
	s_add_i32 s75, s8, 0xffffff40
	s_mov_b32 s33, 64
	s_branch .Lhlp_entry
.Lhlp_return:
	s_waitcnt vmcnt(0) lgkmcnt(0)
	v_readlane_b32 s2, v239, 40
	s_mov_b32 m0, s2
	v_readlane_b32 s0, v238, 0
	v_readlane_b32 s1, v238, 1
	v_readlane_b32 s2, v238, 2
	v_readlane_b32 s3, v238, 3
	v_readlane_b32 s4, v238, 4
	v_readlane_b32 s5, v238, 5
	v_readlane_b32 s6, v238, 6
	v_readlane_b32 s7, v238, 7
	v_readlane_b32 s8, v238, 8
	v_readlane_b32 s9, v238, 9
	v_readlane_b32 s10, v238, 10
	v_readlane_b32 s11, v238, 11
	v_readlane_b32 s12, v238, 12
	v_readlane_b32 s13, v238, 13
	v_readlane_b32 s14, v238, 14
	v_readlane_b32 s15, v238, 15
	v_readlane_b32 s16, v238, 16
	v_readlane_b32 s17, v238, 17
	v_readlane_b32 s18, v238, 18
	v_readlane_b32 s19, v238, 19
	v_readlane_b32 s20, v238, 20
	v_readlane_b32 s21, v238, 21
	v_readlane_b32 s22, v238, 22
	v_readlane_b32 s23, v238, 23
	v_readlane_b32 s24, v238, 24
	v_readlane_b32 s25, v238, 25
	v_readlane_b32 s26, v238, 26
	v_readlane_b32 s27, v238, 27
	v_readlane_b32 s28, v238, 28
	v_readlane_b32 s29, v238, 29
	v_readlane_b32 s30, v238, 30
	v_readlane_b32 s31, v238, 31
	v_readlane_b32 s32, v238, 32
	v_readlane_b32 s33, v238, 33
	v_readlane_b32 s34, v238, 34
	v_readlane_b32 s35, v238, 35
	v_readlane_b32 s36, v238, 36
	v_readlane_b32 s37, v238, 37
	v_readlane_b32 s38, v238, 38
	v_readlane_b32 s39, v238, 39
	v_readlane_b32 s40, v238, 40
	v_readlane_b32 s41, v238, 41
	v_readlane_b32 s42, v238, 42
	v_readlane_b32 s43, v238, 43
	v_readlane_b32 s44, v238, 44
	v_readlane_b32 s45, v238, 45
	v_readlane_b32 s46, v238, 46
	v_readlane_b32 s47, v238, 47
	v_readlane_b32 s48, v238, 48
	v_readlane_b32 s49, v238, 49
	v_readlane_b32 s50, v238, 50
	v_readlane_b32 s51, v238, 51
	v_readlane_b32 s52, v238, 52
	v_readlane_b32 s53, v238, 53
	v_readlane_b32 s54, v238, 54
	v_readlane_b32 s55, v238, 55
	v_readlane_b32 s56, v238, 56
	v_readlane_b32 s57, v238, 57
	v_readlane_b32 s58, v238, 58
	v_readlane_b32 s59, v238, 59
	v_readlane_b32 s60, v238, 60
	v_readlane_b32 s61, v238, 61
	v_readlane_b32 s62, v238, 62
	v_readlane_b32 s63, v238, 63
	v_readlane_b32 s64, v239, 0
	v_readlane_b32 s65, v239, 1
	v_readlane_b32 s66, v239, 2
	v_readlane_b32 s67, v239, 3
	v_readlane_b32 s68, v239, 4
	v_readlane_b32 s69, v239, 5
	v_readlane_b32 s70, v239, 6
	v_readlane_b32 s71, v239, 7
	v_readlane_b32 s72, v239, 8
	v_readlane_b32 s73, v239, 9
	v_readlane_b32 s74, v239, 10
	v_readlane_b32 s75, v239, 11
	v_readlane_b32 s76, v239, 12
	v_readlane_b32 s77, v239, 13
	v_readlane_b32 s78, v239, 14
	v_readlane_b32 s79, v239, 15
	v_readlane_b32 s80, v239, 16
	v_readlane_b32 s81, v239, 17
	v_readlane_b32 s82, v239, 18
	v_readlane_b32 s83, v239, 19
	v_readlane_b32 s84, v239, 20
	v_readlane_b32 s85, v239, 21
	v_readlane_b32 s86, v239, 22
	v_readlane_b32 s87, v239, 23
	v_readlane_b32 s88, v239, 24
	v_readlane_b32 s89, v239, 25
	v_readlane_b32 s90, v239, 26
	v_readlane_b32 s91, v239, 27
	v_readlane_b32 s92, v239, 28
	v_readlane_b32 s93, v239, 29
	v_readlane_b32 s94, v239, 30
	v_readlane_b32 s95, v239, 31
	v_readlane_b32 s96, v239, 32
	v_readlane_b32 s97, v239, 33
	v_readlane_b32 s98, v239, 34
	v_readlane_b32 s99, v239, 35
	v_readlane_b32 s100, v239, 36
	v_readlane_b32 s101, v239, 37
	v_readlane_b32 vcc_lo, v239, 38
	v_readlane_b32 vcc_hi, v239, 39
